# sel score loops: paired vmcnt/lgkmcnt waits merged (one wait per staging pair / MFMA pair)
# speedup vs baseline: 1.0044x; 1.0019x over previous
.LBB0_820:
	s_add_i32 s40, s8, -3
	s_min_i32 s9, s40, s7
	s_lshl_b32 s98, s9, 15
	s_waitcnt vmcnt(12)
	v_lshl_add_u64 v[60:61], v[244:245], 0, s[98:99]
	global_load_dwordx4 v[88:91], v[60:61], off
	global_load_dwordx4 v[92:95], v[60:61], off offset:1024
	global_load_dwordx4 v[56:59], v[60:61], off offset:2048
	s_nop 0
	global_load_dwordx4 v[60:63], v[60:61], off offset:3072
	v_add_u32_e32 v103, v178, v98
	s_waitcnt vmcnt(14)
	ds_write_b128 v103, v[64:67]
	ds_write_b128 v103, v[68:71] offset:1152
	v_add_u32_e32 v107, v179, v96
	ds_read_b128 v[64:67], v107
	ds_read_b128 v[68:71], v107 offset:64
	s_waitcnt vmcnt(12)
	ds_write_b128 v103, v[32:35]
	ds_write_b128 v103, v[36:39] offset:1152
	ds_read_b128 v[32:35], v107
	ds_read_b128 v[36:39], v107 offset:64
	s_waitcnt lgkmcnt(4)
	v_mfma_f32_16x16x32_bf16 v[108:111], v[0:3], v[64:67], 0
	v_mfma_f32_16x16x32_bf16 v[112:115], v[8:11], v[64:67], 0
	v_mfma_f32_16x16x32_bf16 v[108:111], v[4:7], v[68:71], v[108:111]
	v_mfma_f32_16x16x32_bf16 v[112:115], v[12:15], v[68:71], v[112:115]
	v_mfma_f32_16x16x32_bf16 v[116:119], v[16:19], v[64:67], 0
	s_nop 5
	v_max_f32_e32 v108, 0, v108
	v_fma_f32 v120, v162, v108, 0
	v_max_f32_e32 v108, 0, v109
	v_max_f32_e32 v112, 0, v112
	v_fmac_f32_e32 v120, v163, v108
	v_fma_f32 v112, v166, v112, 0
	v_max_f32_e32 v108, 0, v113
	v_fmac_f32_e32 v112, v167, v108
	v_max_f32_e32 v108, 0, v110
	v_fmac_f32_e32 v120, v164, v108
	v_mfma_f32_16x16x32_bf16 v[64:67], v[24:27], v[64:67], 0
	v_max_f32_e32 v108, 0, v114
	v_fmac_f32_e32 v112, v168, v108
	v_max_f32_e32 v108, 0, v111
	v_fmac_f32_e32 v120, v165, v108
	v_mfma_f32_16x16x32_bf16 v[64:67], v[28:31], v[68:71], v[64:67]
	v_max_f32_e32 v113, 0, v115
	v_fmac_f32_e32 v112, v169, v113
	v_add_f32_e32 v112, v120, v112
	v_mfma_f32_16x16x32_bf16 v[108:111], v[20:23], v[68:71], v[116:119]
	ds_write_b32 v99, v112
	s_nop 2
	v_max_f32_e32 v64, 0, v64
	v_fma_f32 v64, v174, v64, 0
	s_nop 1
	v_max_f32_e32 v68, 0, v108
	v_max_f32_e32 v65, 0, v65
	v_fma_f32 v68, v170, v68, 0
	v_max_f32_e32 v69, 0, v109
	v_fmac_f32_e32 v64, v175, v65
	v_fmac_f32_e32 v68, v171, v69
	v_max_f32_e32 v65, 0, v110
	v_fmac_f32_e32 v68, v172, v65
	v_max_f32_e32 v65, 0, v66
	v_fmac_f32_e32 v64, v176, v65
	v_max_f32_e32 v65, 0, v111
	v_fmac_f32_e32 v68, v173, v65
	v_max_f32_e32 v65, 0, v67
	v_fmac_f32_e32 v64, v177, v65
	v_add_f32_e32 v64, v68, v64
	ds_write_b32 v246, v64
	s_waitcnt lgkmcnt(2)
	v_mfma_f32_16x16x32_bf16 v[64:67], v[0:3], v[32:35], 0
	v_mfma_f32_16x16x32_bf16 v[68:71], v[8:11], v[32:35], 0
	v_mfma_f32_16x16x32_bf16 v[64:67], v[4:7], v[36:39], v[64:67]
	v_mfma_f32_16x16x32_bf16 v[68:71], v[12:15], v[36:39], v[68:71]
	v_mfma_f32_16x16x32_bf16 v[108:111], v[16:19], v[32:35], 0
	s_nop 5
	v_max_f32_e32 v64, 0, v64
	v_fma_f32 v112, v162, v64, 0
	v_max_f32_e32 v64, 0, v68
	v_fma_f32 v68, v166, v64, 0
	v_max_f32_e32 v64, 0, v65
	v_fmac_f32_e32 v112, v163, v64
	v_max_f32_e32 v64, 0, v69
	v_fmac_f32_e32 v68, v167, v64
	v_max_f32_e32 v64, 0, v66
	v_fmac_f32_e32 v112, v164, v64
	v_mfma_f32_16x16x32_bf16 v[32:35], v[24:27], v[32:35], 0
	v_max_f32_e32 v64, 0, v70
	v_fmac_f32_e32 v68, v168, v64
	v_max_f32_e32 v64, 0, v67
	v_fmac_f32_e32 v112, v165, v64
	v_mfma_f32_16x16x32_bf16 v[32:35], v[28:31], v[36:39], v[32:35]
	v_max_f32_e32 v69, 0, v71
	v_fmac_f32_e32 v68, v169, v69
	v_add_f32_e32 v68, v112, v68
	v_mfma_f32_16x16x32_bf16 v[64:67], v[20:23], v[36:39], v[108:111]
	ds_write_b32 v99, v68 offset:64
	s_nop 2
	v_max_f32_e32 v32, 0, v32
	v_fma_f32 v32, v174, v32, 0
	s_nop 1
	v_max_f32_e32 v36, 0, v64
	v_max_f32_e32 v33, 0, v33
	v_fma_f32 v36, v170, v36, 0
	v_max_f32_e32 v37, 0, v65
	v_fmac_f32_e32 v32, v175, v33
	v_fmac_f32_e32 v36, v171, v37
	v_max_f32_e32 v33, 0, v66
	v_fmac_f32_e32 v36, v172, v33
	v_max_f32_e32 v33, 0, v34
	v_fmac_f32_e32 v32, v176, v33
	v_max_f32_e32 v33, 0, v67
	v_fmac_f32_e32 v36, v173, v33
	v_max_f32_e32 v33, 0, v35
	v_fmac_f32_e32 v32, v177, v33
	v_add_f32_e32 v32, v36, v32
	ds_write_b32 v246, v32 offset:64
	s_add_i32 s9, s8, -2
	s_min_i32 s57, s9, s7
	s_lshl_b32 s98, s57, 15
	v_lshl_add_u64 v[36:37], v[244:245], 0, s[98:99]
	global_load_dwordx4 v[64:67], v[36:37], off
	global_load_dwordx4 v[68:71], v[36:37], off offset:1024
	global_load_dwordx4 v[32:35], v[36:37], off offset:2048
	s_nop 0
	global_load_dwordx4 v[36:39], v[36:37], off offset:3072
	s_add_i32 s57, s8, -5
	s_cmp_ge_i32 s57, s6
	s_cbranch_scc1 .LBB0_822
	s_waitcnt vmcnt(14)
	ds_write_b128 v103, v[72:75]
	ds_write_b128 v103, v[76:79] offset:1152
	ds_read_b128 v[72:75], v107
	ds_read_b128 v[76:79], v107 offset:64
	s_waitcnt vmcnt(12)
	ds_write_b128 v103, v[40:43]
	ds_write_b128 v103, v[44:47] offset:1152
	ds_read_b128 v[40:43], v107
	ds_read_b128 v[44:47], v107 offset:64
	s_waitcnt lgkmcnt(4)
	v_mfma_f32_16x16x32_bf16 v[108:111], v[0:3], v[72:75], 0
	v_mfma_f32_16x16x32_bf16 v[112:115], v[8:11], v[72:75], 0
	v_mfma_f32_16x16x32_bf16 v[108:111], v[4:7], v[76:79], v[108:111]
	v_mfma_f32_16x16x32_bf16 v[112:115], v[12:15], v[76:79], v[112:115]
	v_mfma_f32_16x16x32_bf16 v[116:119], v[16:19], v[72:75], 0
	s_nop 5
	v_max_f32_e32 v108, 0, v108
	v_fma_f32 v120, v162, v108, 0
	v_max_f32_e32 v108, 0, v109
	v_max_f32_e32 v112, 0, v112
	v_fmac_f32_e32 v120, v163, v108
	v_fma_f32 v112, v166, v112, 0
	v_max_f32_e32 v108, 0, v113
	v_fmac_f32_e32 v112, v167, v108
	v_max_f32_e32 v108, 0, v110
	v_fmac_f32_e32 v120, v164, v108
	v_mfma_f32_16x16x32_bf16 v[72:75], v[24:27], v[72:75], 0
	v_max_f32_e32 v108, 0, v114
	v_fmac_f32_e32 v112, v168, v108
	v_max_f32_e32 v108, 0, v111
	v_fmac_f32_e32 v120, v165, v108
	v_mfma_f32_16x16x32_bf16 v[72:75], v[28:31], v[76:79], v[72:75]
	v_max_f32_e32 v113, 0, v115
	v_fmac_f32_e32 v112, v169, v113
	v_add_f32_e32 v112, v120, v112
	v_mfma_f32_16x16x32_bf16 v[108:111], v[20:23], v[76:79], v[116:119]
	ds_write_b32 v99, v112 offset:1024
	s_nop 2
	v_max_f32_e32 v72, 0, v72
	v_fma_f32 v72, v174, v72, 0
	s_nop 1
	v_max_f32_e32 v76, 0, v108
	v_max_f32_e32 v73, 0, v73
	v_fma_f32 v76, v170, v76, 0
	v_max_f32_e32 v77, 0, v109
	v_fmac_f32_e32 v72, v175, v73
	v_fmac_f32_e32 v76, v171, v77
	v_max_f32_e32 v73, 0, v110
	v_fmac_f32_e32 v76, v172, v73
	v_max_f32_e32 v73, 0, v74
	v_fmac_f32_e32 v72, v176, v73
	v_max_f32_e32 v73, 0, v111
	v_fmac_f32_e32 v76, v173, v73
	v_max_f32_e32 v73, 0, v75
	v_fmac_f32_e32 v72, v177, v73
	v_add_f32_e32 v72, v76, v72
	ds_write_b32 v246, v72 offset:1024
	s_waitcnt lgkmcnt(2)
	v_mfma_f32_16x16x32_bf16 v[72:75], v[0:3], v[40:43], 0
	v_mfma_f32_16x16x32_bf16 v[76:79], v[8:11], v[40:43], 0
	v_mfma_f32_16x16x32_bf16 v[72:75], v[4:7], v[44:47], v[72:75]
	v_mfma_f32_16x16x32_bf16 v[76:79], v[12:15], v[44:47], v[76:79]
	v_mfma_f32_16x16x32_bf16 v[108:111], v[16:19], v[40:43], 0
	s_nop 5
	v_max_f32_e32 v72, 0, v72
	v_fma_f32 v112, v162, v72, 0
	v_max_f32_e32 v72, 0, v76
	v_fma_f32 v76, v166, v72, 0
	v_max_f32_e32 v72, 0, v73
	v_fmac_f32_e32 v112, v163, v72
	v_max_f32_e32 v72, 0, v77
	v_fmac_f32_e32 v76, v167, v72
	v_max_f32_e32 v72, 0, v74
	v_fmac_f32_e32 v112, v164, v72
	v_mfma_f32_16x16x32_bf16 v[40:43], v[24:27], v[40:43], 0
	v_max_f32_e32 v72, 0, v78
	v_fmac_f32_e32 v76, v168, v72
	v_max_f32_e32 v72, 0, v75
	v_fmac_f32_e32 v112, v165, v72
	v_mfma_f32_16x16x32_bf16 v[40:43], v[28:31], v[44:47], v[40:43]
	v_max_f32_e32 v77, 0, v79
	v_fmac_f32_e32 v76, v169, v77
	v_add_f32_e32 v76, v112, v76
	v_mfma_f32_16x16x32_bf16 v[72:75], v[20:23], v[44:47], v[108:111]
	ds_write_b32 v99, v76 offset:1088
	s_nop 2
	v_max_f32_e32 v40, 0, v40
	v_fma_f32 v40, v174, v40, 0
	s_nop 1
	v_max_f32_e32 v44, 0, v72
	v_max_f32_e32 v41, 0, v41
	v_fma_f32 v44, v170, v44, 0
	v_max_f32_e32 v45, 0, v73
	v_fmac_f32_e32 v40, v175, v41
	v_fmac_f32_e32 v44, v171, v45
	v_max_f32_e32 v41, 0, v74
	v_fmac_f32_e32 v44, v172, v41
	v_max_f32_e32 v41, 0, v42
	v_fmac_f32_e32 v40, v176, v41
	v_max_f32_e32 v41, 0, v75
	v_fmac_f32_e32 v44, v173, v41
	v_max_f32_e32 v41, 0, v43
	v_fmac_f32_e32 v40, v177, v41
	v_add_f32_e32 v40, v44, v40
	ds_write_b32 v246, v40 offset:1088
.LBB0_822:
	s_add_i32 s57, s8, -1
	s_min_i32 s57, s57, s7
	s_lshl_b32 s98, s57, 15
	s_waitcnt vmcnt(12)
	v_lshl_add_u64 v[44:45], v[244:245], 0, s[98:99]
	global_load_dwordx4 v[72:75], v[44:45], off
	global_load_dwordx4 v[76:79], v[44:45], off offset:1024
	global_load_dwordx4 v[40:43], v[44:45], off offset:2048
	s_nop 0
	global_load_dwordx4 v[44:47], v[44:45], off offset:3072
	s_add_i32 s57, s8, -4
	s_cmp_ge_i32 s57, s6
	s_cbranch_scc1 .LBB0_824
	s_waitcnt vmcnt(14)
	ds_write_b128 v103, v[80:83]
	ds_write_b128 v103, v[84:87] offset:1152
	ds_read_b128 v[80:83], v107
	ds_read_b128 v[84:87], v107 offset:64
	s_waitcnt vmcnt(12)
	ds_write_b128 v103, v[48:51]
	ds_write_b128 v103, v[52:55] offset:1152
	ds_read_b128 v[48:51], v107
	ds_read_b128 v[52:55], v107 offset:64
	s_waitcnt lgkmcnt(4)
	v_mfma_f32_16x16x32_bf16 v[108:111], v[0:3], v[80:83], 0
	v_mfma_f32_16x16x32_bf16 v[112:115], v[8:11], v[80:83], 0
	v_mfma_f32_16x16x32_bf16 v[108:111], v[4:7], v[84:87], v[108:111]
	v_mfma_f32_16x16x32_bf16 v[112:115], v[12:15], v[84:87], v[112:115]
	v_mfma_f32_16x16x32_bf16 v[116:119], v[16:19], v[80:83], 0
	s_nop 5
	v_max_f32_e32 v108, 0, v108
	v_fma_f32 v120, v162, v108, 0
	v_max_f32_e32 v108, 0, v109
	v_max_f32_e32 v112, 0, v112
	v_fmac_f32_e32 v120, v163, v108
	v_fma_f32 v112, v166, v112, 0
	v_max_f32_e32 v108, 0, v113
	v_fmac_f32_e32 v112, v167, v108
	v_max_f32_e32 v108, 0, v110
	v_fmac_f32_e32 v120, v164, v108
	v_mfma_f32_16x16x32_bf16 v[80:83], v[24:27], v[80:83], 0
	v_max_f32_e32 v108, 0, v114
	v_fmac_f32_e32 v112, v168, v108
	v_max_f32_e32 v108, 0, v111
	v_fmac_f32_e32 v120, v165, v108
	v_mfma_f32_16x16x32_bf16 v[80:83], v[28:31], v[84:87], v[80:83]
	v_max_f32_e32 v113, 0, v115
	v_fmac_f32_e32 v112, v169, v113
	v_add_f32_e32 v112, v120, v112
	v_mfma_f32_16x16x32_bf16 v[108:111], v[20:23], v[84:87], v[116:119]
	ds_write_b32 v99, v112 offset:2048
	s_nop 2
	v_max_f32_e32 v80, 0, v80
	v_fma_f32 v80, v174, v80, 0
	s_nop 1
	v_max_f32_e32 v84, 0, v108
	v_max_f32_e32 v81, 0, v81
	v_fma_f32 v84, v170, v84, 0
	v_max_f32_e32 v85, 0, v109
	v_fmac_f32_e32 v80, v175, v81
	v_fmac_f32_e32 v84, v171, v85
	v_max_f32_e32 v81, 0, v110
	v_fmac_f32_e32 v84, v172, v81
	v_max_f32_e32 v81, 0, v82
	v_fmac_f32_e32 v80, v176, v81
	v_max_f32_e32 v81, 0, v111
	v_fmac_f32_e32 v84, v173, v81
	v_max_f32_e32 v81, 0, v83
	v_fmac_f32_e32 v80, v177, v81
	v_add_f32_e32 v80, v84, v80
	ds_write_b32 v246, v80 offset:2048
	s_waitcnt lgkmcnt(2)
	v_mfma_f32_16x16x32_bf16 v[80:83], v[0:3], v[48:51], 0
	v_mfma_f32_16x16x32_bf16 v[84:87], v[8:11], v[48:51], 0
	v_mfma_f32_16x16x32_bf16 v[80:83], v[4:7], v[52:55], v[80:83]
	v_mfma_f32_16x16x32_bf16 v[84:87], v[12:15], v[52:55], v[84:87]
	v_mfma_f32_16x16x32_bf16 v[108:111], v[16:19], v[48:51], 0
	s_nop 5
	v_max_f32_e32 v80, 0, v80
	v_fma_f32 v112, v162, v80, 0
	v_max_f32_e32 v80, 0, v84
	v_fma_f32 v84, v166, v80, 0
	v_max_f32_e32 v80, 0, v81
	v_fmac_f32_e32 v112, v163, v80
	v_max_f32_e32 v80, 0, v85
	v_fmac_f32_e32 v84, v167, v80
	v_max_f32_e32 v80, 0, v82
	v_fmac_f32_e32 v112, v164, v80
	v_mfma_f32_16x16x32_bf16 v[48:51], v[24:27], v[48:51], 0
	v_max_f32_e32 v80, 0, v86
	v_fmac_f32_e32 v84, v168, v80
	v_max_f32_e32 v80, 0, v83
	v_fmac_f32_e32 v112, v165, v80
	v_mfma_f32_16x16x32_bf16 v[48:51], v[28:31], v[52:55], v[48:51]
	v_max_f32_e32 v85, 0, v87
	v_fmac_f32_e32 v84, v169, v85
	v_add_f32_e32 v84, v112, v84
	v_mfma_f32_16x16x32_bf16 v[80:83], v[20:23], v[52:55], v[108:111]
	ds_write_b32 v99, v84 offset:2112
	s_nop 2
	v_max_f32_e32 v48, 0, v48
	v_fma_f32 v48, v174, v48, 0
	s_nop 1
	v_max_f32_e32 v52, 0, v80
	v_max_f32_e32 v49, 0, v49
	v_fma_f32 v52, v170, v52, 0
	v_max_f32_e32 v53, 0, v81
	v_fmac_f32_e32 v48, v175, v49
	v_fmac_f32_e32 v52, v171, v53
	v_max_f32_e32 v49, 0, v82
	v_fmac_f32_e32 v52, v172, v49
	v_max_f32_e32 v49, 0, v50
	v_fmac_f32_e32 v48, v176, v49
	v_max_f32_e32 v49, 0, v83
	v_fmac_f32_e32 v52, v173, v49
	v_max_f32_e32 v49, 0, v51
	v_fmac_f32_e32 v48, v177, v49
	v_add_f32_e32 v48, v52, v48
	ds_write_b32 v246, v48 offset:2112
.LBB0_824:
	s_min_i32 s57, s8, s7
	s_lshl_b32 s98, s57, 15
	s_cmp_ge_i32 s40, s6
	s_waitcnt vmcnt(12)
	v_lshl_add_u64 v[52:53], v[244:245], 0, s[98:99]
	global_load_dwordx4 v[80:83], v[52:53], off
	global_load_dwordx4 v[84:87], v[52:53], off offset:1024
	global_load_dwordx4 v[48:51], v[52:53], off offset:2048
	s_nop 0
	global_load_dwordx4 v[52:55], v[52:53], off offset:3072
	s_cbranch_scc1 .LBB0_819
	s_waitcnt vmcnt(14)
	ds_write_b128 v103, v[88:91]
	ds_write_b128 v103, v[92:95] offset:1152
	ds_read_b128 v[88:91], v107
	ds_read_b128 v[92:95], v107 offset:64
	s_waitcnt vmcnt(12)
	ds_write_b128 v103, v[56:59]
	ds_write_b128 v103, v[60:63] offset:1152
	ds_read_b128 v[56:59], v107
	ds_read_b128 v[60:63], v107 offset:64
	s_waitcnt lgkmcnt(4)
	v_mfma_f32_16x16x32_bf16 v[108:111], v[0:3], v[88:91], 0
	v_mfma_f32_16x16x32_bf16 v[112:115], v[8:11], v[88:91], 0
	v_mfma_f32_16x16x32_bf16 v[108:111], v[4:7], v[92:95], v[108:111]
	v_mfma_f32_16x16x32_bf16 v[112:115], v[12:15], v[92:95], v[112:115]
	v_mfma_f32_16x16x32_bf16 v[116:119], v[16:19], v[88:91], 0
	s_nop 5
	v_max_f32_e32 v108, 0, v108
	v_fma_f32 v120, v162, v108, 0
	v_max_f32_e32 v108, 0, v109
	v_max_f32_e32 v112, 0, v112
	v_fmac_f32_e32 v120, v163, v108
	v_fma_f32 v112, v166, v112, 0
	v_max_f32_e32 v108, 0, v113
	v_fmac_f32_e32 v112, v167, v108
	v_max_f32_e32 v108, 0, v110
	v_fmac_f32_e32 v120, v164, v108
	v_mfma_f32_16x16x32_bf16 v[88:91], v[24:27], v[88:91], 0
	v_max_f32_e32 v108, 0, v114
	v_fmac_f32_e32 v112, v168, v108
	v_max_f32_e32 v108, 0, v111
	v_fmac_f32_e32 v120, v165, v108
	v_mfma_f32_16x16x32_bf16 v[88:91], v[28:31], v[92:95], v[88:91]
	v_max_f32_e32 v113, 0, v115
	v_fmac_f32_e32 v112, v169, v113
	v_add_f32_e32 v112, v120, v112
	v_mfma_f32_16x16x32_bf16 v[108:111], v[20:23], v[92:95], v[116:119]
	ds_write_b32 v99, v112 offset:3072
	s_nop 2
	v_max_f32_e32 v88, 0, v88
	v_fma_f32 v88, v174, v88, 0
	s_nop 1
	v_max_f32_e32 v92, 0, v108
	v_max_f32_e32 v89, 0, v89
	v_fma_f32 v92, v170, v92, 0
	v_max_f32_e32 v93, 0, v109
	v_fmac_f32_e32 v88, v175, v89
	v_fmac_f32_e32 v92, v171, v93
	v_max_f32_e32 v89, 0, v110
	v_fmac_f32_e32 v92, v172, v89
	v_max_f32_e32 v89, 0, v90
	v_fmac_f32_e32 v88, v176, v89
	v_max_f32_e32 v89, 0, v111
	v_fmac_f32_e32 v92, v173, v89
	v_max_f32_e32 v89, 0, v91
	v_fmac_f32_e32 v88, v177, v89
	v_add_f32_e32 v88, v92, v88
	ds_write_b32 v246, v88 offset:3072
	s_waitcnt lgkmcnt(2)
	v_mfma_f32_16x16x32_bf16 v[88:91], v[0:3], v[56:59], 0
	v_mfma_f32_16x16x32_bf16 v[92:95], v[8:11], v[56:59], 0
	v_mfma_f32_16x16x32_bf16 v[88:91], v[4:7], v[60:63], v[88:91]
	v_mfma_f32_16x16x32_bf16 v[92:95], v[12:15], v[60:63], v[92:95]
	v_mfma_f32_16x16x32_bf16 v[108:111], v[16:19], v[56:59], 0
	s_nop 5
	v_max_f32_e32 v88, 0, v88
	v_fma_f32 v103, v162, v88, 0
	v_max_f32_e32 v88, 0, v92
	v_fma_f32 v92, v166, v88, 0
	v_max_f32_e32 v88, 0, v89
	v_fmac_f32_e32 v103, v163, v88
	v_max_f32_e32 v88, 0, v93
	v_fmac_f32_e32 v92, v167, v88
	v_max_f32_e32 v88, 0, v90
	v_fmac_f32_e32 v103, v164, v88
	v_mfma_f32_16x16x32_bf16 v[56:59], v[24:27], v[56:59], 0
	v_max_f32_e32 v88, 0, v94
	v_fmac_f32_e32 v92, v168, v88
	v_max_f32_e32 v88, 0, v91
	v_fmac_f32_e32 v103, v165, v88
	v_mfma_f32_16x16x32_bf16 v[56:59], v[28:31], v[60:63], v[56:59]
	v_max_f32_e32 v93, 0, v95
	v_fmac_f32_e32 v92, v169, v93
	v_add_f32_e32 v92, v103, v92
	v_mfma_f32_16x16x32_bf16 v[88:91], v[20:23], v[60:63], v[108:111]
	ds_write_b32 v99, v92 offset:3136
	s_nop 2
	v_max_f32_e32 v56, 0, v56
	v_fma_f32 v56, v174, v56, 0
	s_nop 1
	v_max_f32_e32 v60, 0, v88
	v_max_f32_e32 v57, 0, v57
	v_fma_f32 v60, v170, v60, 0
	v_max_f32_e32 v61, 0, v89
	v_fmac_f32_e32 v56, v175, v57
	v_fmac_f32_e32 v60, v171, v61
	v_max_f32_e32 v57, 0, v90
	v_fmac_f32_e32 v60, v172, v57
	v_max_f32_e32 v57, 0, v58
	v_fmac_f32_e32 v56, v176, v57
	v_max_f32_e32 v57, 0, v91
	v_fmac_f32_e32 v60, v173, v57
	v_max_f32_e32 v57, 0, v59
	v_fmac_f32_e32 v56, v177, v57
	v_add_f32_e32 v56, v60, v56
	ds_write_b32 v246, v56 offset:3136
	s_branch .LBB0_819

.LBB0_834:
	s_add_i32 s40, s8, -3
	s_min_i32 s9, s40, s7
	s_lshl_b32 s98, s9, 15
	s_waitcnt vmcnt(12)
	v_lshl_add_u64 v[60:61], v[244:245], 0, s[98:99]
	global_load_dwordx4 v[88:91], v[60:61], off
	global_load_dwordx4 v[92:95], v[60:61], off offset:1024
	global_load_dwordx4 v[56:59], v[60:61], off offset:2048
	s_nop 0
	global_load_dwordx4 v[60:63], v[60:61], off offset:3072
	v_add_u32_e32 v103, v178, v98
	s_waitcnt vmcnt(14)
	ds_write_b128 v103, v[64:67]
	ds_write_b128 v103, v[68:71] offset:1152
	v_add_u32_e32 v191, v179, v96
	ds_read_b128 v[64:67], v191
	ds_read_b128 v[68:71], v191 offset:64
	s_waitcnt vmcnt(12)
	ds_write_b128 v103, v[32:35]
	ds_write_b128 v103, v[36:39] offset:1152
	ds_read_b128 v[32:35], v191
	ds_read_b128 v[36:39], v191 offset:64
	s_waitcnt lgkmcnt(4)
	v_mfma_f32_16x16x32_bf16 v[196:199], v[0:3], v[64:67], 0
	v_mfma_f32_16x16x32_bf16 v[200:203], v[8:11], v[64:67], 0
	v_mfma_f32_16x16x32_bf16 v[196:199], v[4:7], v[68:71], v[196:199]
	v_mfma_f32_16x16x32_bf16 v[200:203], v[12:15], v[68:71], v[200:203]
	v_mfma_f32_16x16x32_bf16 v[204:207], v[16:19], v[64:67], 0
	s_nop 5
	v_max_f32_e32 v192, 0, v196
	v_fma_f32 v192, v162, v192, 0
	v_max_f32_e32 v195, 0, v197
	v_max_f32_e32 v193, 0, v200
	v_fmac_f32_e32 v192, v163, v195
	v_fma_f32 v193, v166, v193, 0
	v_max_f32_e32 v195, 0, v201
	v_mfma_f32_16x16x32_bf16 v[64:67], v[24:27], v[64:67], 0
	v_fmac_f32_e32 v193, v167, v195
	v_max_f32_e32 v195, 0, v198
	v_fmac_f32_e32 v192, v164, v195
	v_max_f32_e32 v195, 0, v202
	v_mfma_f32_16x16x32_bf16 v[64:67], v[28:31], v[68:71], v[64:67]
	v_fmac_f32_e32 v193, v168, v195
	v_max_f32_e32 v195, 0, v199
	v_mfma_f32_16x16x32_bf16 v[196:199], v[20:23], v[68:71], v[204:207]
	v_fmac_f32_e32 v192, v165, v195
	s_nop 2
	s_nop 0
	v_max_f32_e32 v64, 0, v64
	v_fma_f32 v64, v174, v64, 0
	s_nop 0
	v_max_f32_e32 v68, 0, v196
	v_max_f32_e32 v65, 0, v65
	v_fma_f32 v68, v170, v68, 0
	v_max_f32_e32 v69, 0, v197
	v_fmac_f32_e32 v64, v175, v65
	v_fmac_f32_e32 v68, v171, v69
	v_max_f32_e32 v65, 0, v198
	v_fmac_f32_e32 v68, v172, v65
	v_max_f32_e32 v65, 0, v66
	v_fmac_f32_e32 v64, v176, v65
	v_max_f32_e32 v65, 0, v199
	v_fmac_f32_e32 v68, v173, v65
	v_max_f32_e32 v195, 0, v203
	v_max_f32_e32 v65, 0, v67
	v_fmac_f32_e32 v193, v169, v195
	v_fmac_f32_e32 v64, v177, v65
	v_add_f32_e32 v192, v192, v193
	v_add_f32_e32 v64, v68, v64
	ds_write_b32 v180, v192
	ds_write_b32 v246, v64
	s_waitcnt lgkmcnt(2)
	v_mfma_f32_16x16x32_bf16 v[64:67], v[0:3], v[32:35], 0
	v_mfma_f32_16x16x32_bf16 v[68:71], v[8:11], v[32:35], 0
	v_mfma_f32_16x16x32_bf16 v[64:67], v[4:7], v[36:39], v[64:67]
	v_mfma_f32_16x16x32_bf16 v[68:71], v[12:15], v[36:39], v[68:71]
	v_mfma_f32_16x16x32_bf16 v[196:199], v[16:19], v[32:35], 0
	s_nop 5
	v_max_f32_e32 v64, 0, v64
	v_fma_f32 v192, v162, v64, 0
	v_max_f32_e32 v64, 0, v68
	v_fma_f32 v68, v166, v64, 0
	v_max_f32_e32 v64, 0, v65
	v_fmac_f32_e32 v192, v163, v64
	v_max_f32_e32 v64, 0, v69
	v_fmac_f32_e32 v68, v167, v64
	v_max_f32_e32 v64, 0, v66
	v_fmac_f32_e32 v192, v164, v64
	v_mfma_f32_16x16x32_bf16 v[32:35], v[24:27], v[32:35], 0
	v_max_f32_e32 v64, 0, v70
	v_fmac_f32_e32 v68, v168, v64
	v_max_f32_e32 v64, 0, v67
	v_fmac_f32_e32 v192, v165, v64
	v_mfma_f32_16x16x32_bf16 v[32:35], v[28:31], v[36:39], v[32:35]
	v_max_f32_e32 v69, 0, v71
	v_fmac_f32_e32 v68, v169, v69
	v_add_f32_e32 v68, v192, v68
	v_mfma_f32_16x16x32_bf16 v[64:67], v[20:23], v[36:39], v[196:199]
	ds_write_b32 v180, v68 offset:64
	s_nop 2
	v_max_f32_e32 v32, 0, v32
	v_fma_f32 v32, v174, v32, 0
	s_nop 1
	v_max_f32_e32 v36, 0, v64
	v_max_f32_e32 v33, 0, v33
	v_fma_f32 v36, v170, v36, 0
	v_max_f32_e32 v37, 0, v65
	v_fmac_f32_e32 v32, v175, v33
	v_fmac_f32_e32 v36, v171, v37
	v_max_f32_e32 v33, 0, v66
	v_fmac_f32_e32 v36, v172, v33
	v_max_f32_e32 v33, 0, v34
	v_fmac_f32_e32 v32, v176, v33
	v_max_f32_e32 v33, 0, v67
	v_fmac_f32_e32 v36, v173, v33
	v_max_f32_e32 v33, 0, v35
	v_fmac_f32_e32 v32, v177, v33
	v_add_f32_e32 v32, v36, v32
	ds_write_b32 v246, v32 offset:64
	s_add_i32 s9, s8, -2
	s_min_i32 s57, s9, s7
	s_lshl_b32 s98, s57, 15
	v_lshl_add_u64 v[36:37], v[244:245], 0, s[98:99]
	global_load_dwordx4 v[64:67], v[36:37], off
	global_load_dwordx4 v[68:71], v[36:37], off offset:1024
	global_load_dwordx4 v[32:35], v[36:37], off offset:2048
	s_nop 0
	global_load_dwordx4 v[36:39], v[36:37], off offset:3072
	s_add_i32 s57, s8, -5
	s_cmp_ge_i32 s57, s6
	s_cbranch_scc1 .LBB0_836
	s_waitcnt vmcnt(14)
	ds_write_b128 v103, v[72:75]
	ds_write_b128 v103, v[76:79] offset:1152
	ds_read_b128 v[72:75], v191
	ds_read_b128 v[76:79], v191 offset:64
	s_waitcnt vmcnt(12)
	ds_write_b128 v103, v[40:43]
	ds_write_b128 v103, v[44:47] offset:1152
	ds_read_b128 v[40:43], v191
	ds_read_b128 v[44:47], v191 offset:64
	s_waitcnt lgkmcnt(4)
	v_mfma_f32_16x16x32_bf16 v[196:199], v[0:3], v[72:75], 0
	v_mfma_f32_16x16x32_bf16 v[200:203], v[8:11], v[72:75], 0
	v_mfma_f32_16x16x32_bf16 v[196:199], v[4:7], v[76:79], v[196:199]
	v_mfma_f32_16x16x32_bf16 v[200:203], v[12:15], v[76:79], v[200:203]
	v_mfma_f32_16x16x32_bf16 v[204:207], v[16:19], v[72:75], 0
	s_nop 5
	v_max_f32_e32 v192, 0, v196
	v_fma_f32 v192, v162, v192, 0
	v_max_f32_e32 v195, 0, v197
	v_max_f32_e32 v193, 0, v200
	v_fmac_f32_e32 v192, v163, v195
	v_fma_f32 v193, v166, v193, 0
	v_max_f32_e32 v195, 0, v201
	v_mfma_f32_16x16x32_bf16 v[72:75], v[24:27], v[72:75], 0
	v_fmac_f32_e32 v193, v167, v195
	v_max_f32_e32 v195, 0, v198
	v_fmac_f32_e32 v192, v164, v195
	v_max_f32_e32 v195, 0, v202
	v_mfma_f32_16x16x32_bf16 v[72:75], v[28:31], v[76:79], v[72:75]
	v_fmac_f32_e32 v193, v168, v195
	v_max_f32_e32 v195, 0, v199
	v_mfma_f32_16x16x32_bf16 v[196:199], v[20:23], v[76:79], v[204:207]
	v_fmac_f32_e32 v192, v165, v195
	s_nop 2
	s_nop 0
	v_max_f32_e32 v72, 0, v72
	v_fma_f32 v72, v174, v72, 0
	s_nop 0
	v_max_f32_e32 v76, 0, v196
	v_max_f32_e32 v73, 0, v73
	v_fma_f32 v76, v170, v76, 0
	v_max_f32_e32 v77, 0, v197
	v_fmac_f32_e32 v72, v175, v73
	v_fmac_f32_e32 v76, v171, v77
	v_max_f32_e32 v73, 0, v198
	v_fmac_f32_e32 v76, v172, v73
	v_max_f32_e32 v73, 0, v74
	v_fmac_f32_e32 v72, v176, v73
	v_max_f32_e32 v73, 0, v199
	v_fmac_f32_e32 v76, v173, v73
	v_max_f32_e32 v195, 0, v203
	v_max_f32_e32 v73, 0, v75
	v_fmac_f32_e32 v193, v169, v195
	v_fmac_f32_e32 v72, v177, v73
	v_add_f32_e32 v192, v192, v193
	v_add_f32_e32 v72, v76, v72
	ds_write_b32 v180, v192 offset:1024
	ds_write_b32 v246, v72 offset:1024
	s_waitcnt lgkmcnt(2)
	v_mfma_f32_16x16x32_bf16 v[72:75], v[0:3], v[40:43], 0
	v_mfma_f32_16x16x32_bf16 v[76:79], v[8:11], v[40:43], 0
	v_mfma_f32_16x16x32_bf16 v[72:75], v[4:7], v[44:47], v[72:75]
	v_mfma_f32_16x16x32_bf16 v[76:79], v[12:15], v[44:47], v[76:79]
	v_mfma_f32_16x16x32_bf16 v[196:199], v[16:19], v[40:43], 0
	s_nop 5
	v_max_f32_e32 v72, 0, v72
	v_fma_f32 v192, v162, v72, 0
	v_max_f32_e32 v72, 0, v76
	v_fma_f32 v76, v166, v72, 0
	v_max_f32_e32 v72, 0, v73
	v_fmac_f32_e32 v192, v163, v72
	v_max_f32_e32 v72, 0, v77
	v_fmac_f32_e32 v76, v167, v72
	v_max_f32_e32 v72, 0, v74
	v_fmac_f32_e32 v192, v164, v72
	v_mfma_f32_16x16x32_bf16 v[40:43], v[24:27], v[40:43], 0
	v_max_f32_e32 v72, 0, v78
	v_fmac_f32_e32 v76, v168, v72
	v_max_f32_e32 v72, 0, v75
	v_fmac_f32_e32 v192, v165, v72
	v_mfma_f32_16x16x32_bf16 v[40:43], v[28:31], v[44:47], v[40:43]
	v_max_f32_e32 v77, 0, v79
	v_fmac_f32_e32 v76, v169, v77
	v_add_f32_e32 v76, v192, v76
	v_mfma_f32_16x16x32_bf16 v[72:75], v[20:23], v[44:47], v[196:199]
	ds_write_b32 v180, v76 offset:1088
	s_nop 2
	v_max_f32_e32 v40, 0, v40
	v_fma_f32 v40, v174, v40, 0
	s_nop 1
	v_max_f32_e32 v44, 0, v72
	v_max_f32_e32 v41, 0, v41
	v_fma_f32 v44, v170, v44, 0
	v_max_f32_e32 v45, 0, v73
	v_fmac_f32_e32 v40, v175, v41
	v_fmac_f32_e32 v44, v171, v45
	v_max_f32_e32 v41, 0, v74
	v_fmac_f32_e32 v44, v172, v41
	v_max_f32_e32 v41, 0, v42
	v_fmac_f32_e32 v40, v176, v41
	v_max_f32_e32 v41, 0, v75
	v_fmac_f32_e32 v44, v173, v41
	v_max_f32_e32 v41, 0, v43
	v_fmac_f32_e32 v40, v177, v41
	v_add_f32_e32 v40, v44, v40
	ds_write_b32 v246, v40 offset:1088
.LBB0_836:
	s_add_i32 s57, s8, -1
	s_min_i32 s57, s57, s7
	s_lshl_b32 s98, s57, 15
	s_waitcnt vmcnt(12)
	v_lshl_add_u64 v[44:45], v[244:245], 0, s[98:99]
	global_load_dwordx4 v[72:75], v[44:45], off
	global_load_dwordx4 v[76:79], v[44:45], off offset:1024
	global_load_dwordx4 v[40:43], v[44:45], off offset:2048
	s_nop 0
	global_load_dwordx4 v[44:47], v[44:45], off offset:3072
	s_add_i32 s57, s8, -4
	s_cmp_ge_i32 s57, s6
	s_cbranch_scc1 .LBB0_838
	s_waitcnt vmcnt(14)
	ds_write_b128 v103, v[80:83]
	ds_write_b128 v103, v[84:87] offset:1152
	ds_read_b128 v[80:83], v191
	ds_read_b128 v[84:87], v191 offset:64
	s_waitcnt vmcnt(12)
	ds_write_b128 v103, v[48:51]
	ds_write_b128 v103, v[52:55] offset:1152
	ds_read_b128 v[48:51], v191
	ds_read_b128 v[52:55], v191 offset:64
	s_waitcnt lgkmcnt(4)
	v_mfma_f32_16x16x32_bf16 v[196:199], v[0:3], v[80:83], 0
	v_mfma_f32_16x16x32_bf16 v[200:203], v[8:11], v[80:83], 0
	v_mfma_f32_16x16x32_bf16 v[196:199], v[4:7], v[84:87], v[196:199]
	v_mfma_f32_16x16x32_bf16 v[200:203], v[12:15], v[84:87], v[200:203]
	v_mfma_f32_16x16x32_bf16 v[204:207], v[16:19], v[80:83], 0
	s_nop 5
	v_max_f32_e32 v192, 0, v196
	v_fma_f32 v192, v162, v192, 0
	v_max_f32_e32 v195, 0, v197
	v_max_f32_e32 v193, 0, v200
	v_fmac_f32_e32 v192, v163, v195
	v_fma_f32 v193, v166, v193, 0
	v_max_f32_e32 v195, 0, v201
	v_mfma_f32_16x16x32_bf16 v[80:83], v[24:27], v[80:83], 0
	v_fmac_f32_e32 v193, v167, v195
	v_max_f32_e32 v195, 0, v198
	v_fmac_f32_e32 v192, v164, v195
	v_max_f32_e32 v195, 0, v202
	v_mfma_f32_16x16x32_bf16 v[80:83], v[28:31], v[84:87], v[80:83]
	v_fmac_f32_e32 v193, v168, v195
	v_max_f32_e32 v195, 0, v199
	v_mfma_f32_16x16x32_bf16 v[196:199], v[20:23], v[84:87], v[204:207]
	v_fmac_f32_e32 v192, v165, v195
	s_nop 2
	s_nop 0
	v_max_f32_e32 v80, 0, v80
	v_fma_f32 v80, v174, v80, 0
	s_nop 0
	v_max_f32_e32 v84, 0, v196
	v_max_f32_e32 v81, 0, v81
	v_fma_f32 v84, v170, v84, 0
	v_max_f32_e32 v85, 0, v197
	v_fmac_f32_e32 v80, v175, v81
	v_fmac_f32_e32 v84, v171, v85
	v_max_f32_e32 v81, 0, v198
	v_fmac_f32_e32 v84, v172, v81
	v_max_f32_e32 v81, 0, v82
	v_fmac_f32_e32 v80, v176, v81
	v_max_f32_e32 v81, 0, v199
	v_fmac_f32_e32 v84, v173, v81
	v_max_f32_e32 v195, 0, v203
	v_max_f32_e32 v81, 0, v83
	v_fmac_f32_e32 v193, v169, v195
	v_fmac_f32_e32 v80, v177, v81
	v_add_f32_e32 v192, v192, v193
	v_add_f32_e32 v80, v84, v80
	ds_write_b32 v180, v192 offset:2048
	ds_write_b32 v246, v80 offset:2048
	s_waitcnt lgkmcnt(2)
	v_mfma_f32_16x16x32_bf16 v[80:83], v[0:3], v[48:51], 0
	v_mfma_f32_16x16x32_bf16 v[84:87], v[8:11], v[48:51], 0
	v_mfma_f32_16x16x32_bf16 v[80:83], v[4:7], v[52:55], v[80:83]
	v_mfma_f32_16x16x32_bf16 v[84:87], v[12:15], v[52:55], v[84:87]
	v_mfma_f32_16x16x32_bf16 v[196:199], v[16:19], v[48:51], 0
	s_nop 5
	v_max_f32_e32 v80, 0, v80
	v_fma_f32 v192, v162, v80, 0
	v_max_f32_e32 v80, 0, v84
	v_fma_f32 v84, v166, v80, 0
	v_max_f32_e32 v80, 0, v81
	v_fmac_f32_e32 v192, v163, v80
	v_max_f32_e32 v80, 0, v85
	v_fmac_f32_e32 v84, v167, v80
	v_max_f32_e32 v80, 0, v82
	v_fmac_f32_e32 v192, v164, v80
	v_mfma_f32_16x16x32_bf16 v[48:51], v[24:27], v[48:51], 0
	v_max_f32_e32 v80, 0, v86
	v_fmac_f32_e32 v84, v168, v80
	v_max_f32_e32 v80, 0, v83
	v_fmac_f32_e32 v192, v165, v80
	v_mfma_f32_16x16x32_bf16 v[48:51], v[28:31], v[52:55], v[48:51]
	v_max_f32_e32 v85, 0, v87
	v_fmac_f32_e32 v84, v169, v85
	v_add_f32_e32 v84, v192, v84
	v_mfma_f32_16x16x32_bf16 v[80:83], v[20:23], v[52:55], v[196:199]
	ds_write_b32 v180, v84 offset:2112
	s_nop 2
	v_max_f32_e32 v48, 0, v48
	v_fma_f32 v48, v174, v48, 0
	s_nop 1
	v_max_f32_e32 v52, 0, v80
	v_max_f32_e32 v49, 0, v49
	v_fma_f32 v52, v170, v52, 0
	v_max_f32_e32 v53, 0, v81
	v_fmac_f32_e32 v48, v175, v49
	v_fmac_f32_e32 v52, v171, v53
	v_max_f32_e32 v49, 0, v82
	v_fmac_f32_e32 v52, v172, v49
	v_max_f32_e32 v49, 0, v50
	v_fmac_f32_e32 v48, v176, v49
	v_max_f32_e32 v49, 0, v83
	v_fmac_f32_e32 v52, v173, v49
	v_max_f32_e32 v49, 0, v51
	v_fmac_f32_e32 v48, v177, v49
	v_add_f32_e32 v48, v52, v48
	ds_write_b32 v246, v48 offset:2112
.LBB0_838:
	s_min_i32 s57, s8, s7
	s_lshl_b32 s98, s57, 15
	s_cmp_ge_i32 s40, s6
	s_waitcnt vmcnt(12)
	v_lshl_add_u64 v[52:53], v[244:245], 0, s[98:99]
	global_load_dwordx4 v[80:83], v[52:53], off
	global_load_dwordx4 v[84:87], v[52:53], off offset:1024
	global_load_dwordx4 v[48:51], v[52:53], off offset:2048
	s_nop 0
	global_load_dwordx4 v[52:55], v[52:53], off offset:3072
	s_cbranch_scc1 .LBB0_833
	s_waitcnt vmcnt(14)
	ds_write_b128 v103, v[88:91]
	ds_write_b128 v103, v[92:95] offset:1152
	ds_read_b128 v[88:91], v191
	ds_read_b128 v[92:95], v191 offset:64
	s_waitcnt vmcnt(12)
	ds_write_b128 v103, v[56:59]
	ds_write_b128 v103, v[60:63] offset:1152
	ds_read_b128 v[56:59], v191
	ds_read_b128 v[60:63], v191 offset:64
	s_waitcnt lgkmcnt(4)
	v_mfma_f32_16x16x32_bf16 v[196:199], v[0:3], v[88:91], 0
	v_mfma_f32_16x16x32_bf16 v[200:203], v[8:11], v[88:91], 0
	v_mfma_f32_16x16x32_bf16 v[196:199], v[4:7], v[92:95], v[196:199]
	v_mfma_f32_16x16x32_bf16 v[200:203], v[12:15], v[92:95], v[200:203]
	v_mfma_f32_16x16x32_bf16 v[204:207], v[16:19], v[88:91], 0
	s_nop 5
	v_max_f32_e32 v192, 0, v196
	v_fma_f32 v192, v162, v192, 0
	v_max_f32_e32 v195, 0, v197
	v_max_f32_e32 v193, 0, v200
	v_fmac_f32_e32 v192, v163, v195
	v_fma_f32 v193, v166, v193, 0
	v_max_f32_e32 v195, 0, v201
	v_mfma_f32_16x16x32_bf16 v[88:91], v[24:27], v[88:91], 0
	v_fmac_f32_e32 v193, v167, v195
	v_max_f32_e32 v195, 0, v198
	v_fmac_f32_e32 v192, v164, v195
	v_max_f32_e32 v195, 0, v202
	v_mfma_f32_16x16x32_bf16 v[88:91], v[28:31], v[92:95], v[88:91]
	v_fmac_f32_e32 v193, v168, v195
	v_max_f32_e32 v195, 0, v199
	v_mfma_f32_16x16x32_bf16 v[196:199], v[20:23], v[92:95], v[204:207]
	v_fmac_f32_e32 v192, v165, v195
	s_nop 2
	s_nop 0
	v_max_f32_e32 v88, 0, v88
	v_fma_f32 v88, v174, v88, 0
	s_nop 0
	v_max_f32_e32 v92, 0, v196
	v_max_f32_e32 v89, 0, v89
	v_fma_f32 v92, v170, v92, 0
	v_max_f32_e32 v93, 0, v197
	v_fmac_f32_e32 v88, v175, v89
	v_fmac_f32_e32 v92, v171, v93
	v_max_f32_e32 v89, 0, v198
	v_fmac_f32_e32 v92, v172, v89
	v_max_f32_e32 v89, 0, v90
	v_fmac_f32_e32 v88, v176, v89
	v_max_f32_e32 v89, 0, v199
	v_fmac_f32_e32 v92, v173, v89
	v_max_f32_e32 v195, 0, v203
	v_max_f32_e32 v89, 0, v91
	v_fmac_f32_e32 v193, v169, v195
	v_fmac_f32_e32 v88, v177, v89
	v_add_f32_e32 v192, v192, v193
	v_add_f32_e32 v88, v92, v88
	ds_write_b32 v180, v192 offset:3072
	ds_write_b32 v246, v88 offset:3072
	s_waitcnt lgkmcnt(2)
	v_mfma_f32_16x16x32_bf16 v[88:91], v[0:3], v[56:59], 0
	v_mfma_f32_16x16x32_bf16 v[92:95], v[8:11], v[56:59], 0
	v_mfma_f32_16x16x32_bf16 v[88:91], v[4:7], v[60:63], v[88:91]
	v_mfma_f32_16x16x32_bf16 v[92:95], v[12:15], v[60:63], v[92:95]
	v_mfma_f32_16x16x32_bf16 v[196:199], v[16:19], v[56:59], 0
	s_nop 5
	v_max_f32_e32 v88, 0, v88
	v_fma_f32 v103, v162, v88, 0
	v_max_f32_e32 v88, 0, v92
	v_fma_f32 v92, v166, v88, 0
	v_max_f32_e32 v88, 0, v89
	v_fmac_f32_e32 v103, v163, v88
	v_max_f32_e32 v88, 0, v93
	v_fmac_f32_e32 v92, v167, v88
	v_max_f32_e32 v88, 0, v90
	v_fmac_f32_e32 v103, v164, v88
	v_mfma_f32_16x16x32_bf16 v[56:59], v[24:27], v[56:59], 0
	v_max_f32_e32 v88, 0, v94
	v_fmac_f32_e32 v92, v168, v88
	v_max_f32_e32 v88, 0, v91
	v_fmac_f32_e32 v103, v165, v88
	v_mfma_f32_16x16x32_bf16 v[56:59], v[28:31], v[60:63], v[56:59]
	v_max_f32_e32 v93, 0, v95
	v_fmac_f32_e32 v92, v169, v93
	v_add_f32_e32 v92, v103, v92
	v_mfma_f32_16x16x32_bf16 v[88:91], v[20:23], v[60:63], v[196:199]
	ds_write_b32 v180, v92 offset:3136
	s_nop 2
	v_max_f32_e32 v56, 0, v56
	v_fma_f32 v56, v174, v56, 0
	s_nop 1
	v_max_f32_e32 v60, 0, v88
	v_max_f32_e32 v57, 0, v57
	v_fma_f32 v60, v170, v60, 0
	v_max_f32_e32 v61, 0, v89
	v_fmac_f32_e32 v56, v175, v57
	v_fmac_f32_e32 v60, v171, v61
	v_max_f32_e32 v57, 0, v90
	v_fmac_f32_e32 v60, v172, v57
	v_max_f32_e32 v57, 0, v58
	v_fmac_f32_e32 v56, v176, v57
	v_max_f32_e32 v57, 0, v91
	v_fmac_f32_e32 v60, v173, v57
	v_max_f32_e32 v57, 0, v59
	v_fmac_f32_e32 v56, v177, v57
	v_add_f32_e32 v56, v60, v56
	ds_write_b32 v246, v56 offset:3136
	s_branch .LBB0_833
